# relax first two vmcnt waits after each epilogue (RELAX_EPI) in the three SwiGLU gate-up K-loops
# speedup vs baseline: 1.0113x; 1.0113x over previous
.LBB0_458:
	s_ashr_i32 s43, s42, 31
	s_lshl_b64 s[44:45], s[42:43], 19
	s_add_u32 s44, s64, s44
	s_addc_u32 s45, s65, s45
	s_and_b64 s[46:47], s[40:41], exec
	s_cselect_b32 s31, s45, s17
	s_cselect_b32 s43, s44, s16
	s_ashr_i32 s13, s12, 31
	s_lshl_b64 s[46:47], s[12:13], 19
	s_add_u32 s46, s22, s46
	s_addc_u32 s47, s23, s47
	s_and_b64 s[48:49], s[40:41], exec
	s_cselect_b32 s13, s47, s15
	s_cselect_b32 s50, s46, s14
	s_add_u32 s48, s16, 0x40080
	s_addc_u32 s49, s17, 0
	s_add_u32 s16, s14, 0x100
	v_mov_b32_e32 v0, 0
	s_addc_u32 s17, s15, 0
	s_mov_b32 s51, -2
	v_mov_b32_e32 v1, v0
	v_mov_b32_e32 v2, v0
	v_mov_b32_e32 v3, v0
	v_mov_b32_e32 v8, v0
	v_mov_b32_e32 v9, v0
	v_mov_b32_e32 v10, v0
	v_mov_b32_e32 v11, v0
	v_mov_b32_e32 v16, v0
	v_mov_b32_e32 v17, v0
	v_mov_b32_e32 v18, v0
	v_mov_b32_e32 v19, v0
	v_mov_b32_e32 v24, v0
	v_mov_b32_e32 v25, v0
	v_mov_b32_e32 v26, v0
	v_mov_b32_e32 v27, v0
	v_mov_b32_e32 v32, v0
	v_mov_b32_e32 v33, v0
	v_mov_b32_e32 v34, v0
	v_mov_b32_e32 v35, v0
	v_mov_b32_e32 v40, v0
	v_mov_b32_e32 v41, v0
	v_mov_b32_e32 v42, v0
	v_mov_b32_e32 v43, v0
	v_mov_b32_e32 v48, v0
	v_mov_b32_e32 v49, v0
	v_mov_b32_e32 v50, v0
	v_mov_b32_e32 v51, v0
	v_mov_b32_e32 v56, v0
	v_mov_b32_e32 v57, v0
	v_mov_b32_e32 v58, v0
	v_mov_b32_e32 v59, v0
	v_mov_b32_e32 v4, v0
	v_mov_b32_e32 v5, v0
	v_mov_b32_e32 v6, v0
	v_mov_b32_e32 v7, v0
	v_mov_b32_e32 v12, v0
	v_mov_b32_e32 v13, v0
	v_mov_b32_e32 v14, v0
	v_mov_b32_e32 v15, v0
	v_mov_b32_e32 v20, v0
	v_mov_b32_e32 v21, v0
	v_mov_b32_e32 v22, v0
	v_mov_b32_e32 v23, v0
	v_mov_b32_e32 v28, v0
	v_mov_b32_e32 v29, v0
	v_mov_b32_e32 v30, v0
	v_mov_b32_e32 v31, v0
	v_mov_b32_e32 v36, v0
	v_mov_b32_e32 v37, v0
	v_mov_b32_e32 v38, v0
	v_mov_b32_e32 v39, v0
	v_mov_b32_e32 v44, v0
	v_mov_b32_e32 v45, v0
	v_mov_b32_e32 v46, v0
	v_mov_b32_e32 v47, v0
	v_mov_b32_e32 v52, v0
	v_mov_b32_e32 v53, v0
	v_mov_b32_e32 v54, v0
	v_mov_b32_e32 v55, v0
	v_mov_b32_e32 v60, v0
	v_mov_b32_e32 v61, v0
	v_mov_b32_e32 v62, v0
	v_mov_b32_e32 v63, v0
	v_mov_b32_e32 v64, v0
	v_mov_b32_e32 v65, v0
	v_mov_b32_e32 v66, v0
	v_mov_b32_e32 v67, v0
	v_mov_b32_e32 v72, v0
	v_mov_b32_e32 v73, v0
	v_mov_b32_e32 v74, v0
	v_mov_b32_e32 v75, v0
	v_mov_b32_e32 v80, v0
	v_mov_b32_e32 v81, v0
	v_mov_b32_e32 v82, v0
	v_mov_b32_e32 v83, v0
	v_mov_b32_e32 v88, v0
	v_mov_b32_e32 v89, v0
	v_mov_b32_e32 v90, v0
	v_mov_b32_e32 v91, v0
	v_mov_b32_e32 v96, v0
	v_mov_b32_e32 v97, v0
	v_mov_b32_e32 v98, v0
	v_mov_b32_e32 v99, v0
	v_mov_b32_e32 v104, v0
	v_mov_b32_e32 v105, v0
	v_mov_b32_e32 v106, v0
	v_mov_b32_e32 v107, v0
	v_mov_b32_e32 v112, v0
	v_mov_b32_e32 v113, v0
	v_mov_b32_e32 v114, v0
	v_mov_b32_e32 v115, v0
	v_mov_b32_e32 v120, v0
	v_mov_b32_e32 v121, v0
	v_mov_b32_e32 v122, v0
	v_mov_b32_e32 v123, v0
	v_mov_b32_e32 v68, v0
	v_mov_b32_e32 v69, v0
	v_mov_b32_e32 v70, v0
	v_mov_b32_e32 v71, v0
	v_mov_b32_e32 v76, v0
	v_mov_b32_e32 v77, v0
	v_mov_b32_e32 v78, v0
	v_mov_b32_e32 v79, v0
	v_mov_b32_e32 v84, v0
	v_mov_b32_e32 v85, v0
	v_mov_b32_e32 v86, v0
	v_mov_b32_e32 v87, v0
	v_mov_b32_e32 v92, v0
	v_mov_b32_e32 v93, v0
	v_mov_b32_e32 v94, v0
	v_mov_b32_e32 v95, v0
	v_mov_b32_e32 v100, v0
	v_mov_b32_e32 v101, v0
	v_mov_b32_e32 v102, v0
	v_mov_b32_e32 v103, v0
	v_mov_b32_e32 v108, v0
	v_mov_b32_e32 v109, v0
	v_mov_b32_e32 v110, v0
	v_mov_b32_e32 v111, v0
	v_mov_b32_e32 v116, v0
	v_mov_b32_e32 v117, v0
	v_mov_b32_e32 v118, v0
	v_mov_b32_e32 v119, v0
	v_mov_b32_e32 v124, v0
	v_mov_b32_e32 v125, v0
	v_mov_b32_e32 v126, v0
	v_mov_b32_e32 v127, v0
	s_cmp_lg_u32 s28, 1
	s_cselect_b32 s98, 1, 0
.LBB0_459:
	s_add_u32 s14, s48, 0xfffc0080
	s_addc_u32 s15, s49, -1
	s_add_i32 s70, 0, 0x10000
	s_cmp_eq_u32 s51, 12
	s_cselect_b32 s15, s31, s15
	s_cselect_b32 s14, s43, s14
	v_add_u32_e32 v138, s70, v142
	s_cselect_b32 s61, s13, s17
	s_cselect_b32 s60, s50, s16
	s_add_i32 s84, 0, 0x14000
	ds_read_b128 v[134:137], v138
	ds_read_b128 v[148:151], v138 offset:1024
	ds_read_b128 v[152:155], v138 offset:2048
	ds_read_b128 v[156:159], v138 offset:3072
	v_add_u32_e32 v138, s84, v142
	ds_read_b128 v[160:163], v138
	ds_read_b128 v[164:167], v138 offset:1024
	ds_read_b128 v[168:171], v138 offset:2048
	ds_read_b128 v[172:175], v138 offset:3072
	v_lshl_add_u64 v[138:139], s[48:49], 0, v[132:133]
	s_add_i32 m0, s19, 0xc000
	ds_read_b128 v[176:179], v146
	ds_read_b128 v[180:183], v146 offset:1024
	ds_read_b128 v[194:197], v146 offset:2048
	ds_read_b128 v[198:201], v146 offset:3072
	ds_read_b128 v[202:205], v146 offset:4096
	ds_read_b128 v[206:209], v146 offset:5120
	ds_read_b128 v[210:213], v146 offset:6144
	ds_read_b128 v[214:217], v146 offset:7168
	global_load_lds_dwordx4 v[138:139], off
	v_lshl_add_u64 v[138:139], v[138:139], 0, s[34:35]
	s_add_i32 m0, s19, 0xe000
	s_nop 0
	global_load_lds_dwordx4 v[138:139], off
	s_cmp_eq_u32 s98, 0
	s_cbranch_scc0 .Lrlx459_a
	s_waitcnt vmcnt(8)
.Lrlx459_a_back:
	s_waitcnt lgkmcnt(0)
	s_barrier
	s_setprio 1
	s_waitcnt lgkmcnt(0)
	v_mfma_f32_16x16x32_bf16 v[124:127], v[134:137], v[176:179], v[124:127]
	v_mfma_f32_16x16x32_bf16 v[116:119], v[152:155], v[176:179], v[116:119]
	v_mfma_f32_16x16x32_bf16 v[108:111], v[134:137], v[194:197], v[108:111]
	v_mfma_f32_16x16x32_bf16 v[100:103], v[152:155], v[194:197], v[100:103]
	v_mfma_f32_16x16x32_bf16 v[92:95], v[134:137], v[202:205], v[92:95]
	v_mfma_f32_16x16x32_bf16 v[84:87], v[152:155], v[202:205], v[84:87]
	v_mfma_f32_16x16x32_bf16 v[76:79], v[134:137], v[210:213], v[76:79]
	v_mfma_f32_16x16x32_bf16 v[68:71], v[152:155], v[210:213], v[68:71]
	v_mfma_f32_16x16x32_bf16 v[124:127], v[148:151], v[180:183], v[124:127]
	v_mfma_f32_16x16x32_bf16 v[116:119], v[156:159], v[180:183], v[116:119]
	v_mfma_f32_16x16x32_bf16 v[108:111], v[148:151], v[198:201], v[108:111]
	v_mfma_f32_16x16x32_bf16 v[100:103], v[156:159], v[198:201], v[100:103]
	v_mfma_f32_16x16x32_bf16 v[92:95], v[148:151], v[206:209], v[92:95]
	v_mfma_f32_16x16x32_bf16 v[84:87], v[156:159], v[206:209], v[84:87]
	v_mfma_f32_16x16x32_bf16 v[76:79], v[148:151], v[214:217], v[76:79]
	v_mfma_f32_16x16x32_bf16 v[68:71], v[156:159], v[214:217], v[68:71]
	s_setprio 0
	s_setprio 1
	v_mfma_f32_16x16x32_bf16 v[120:123], v[160:163], v[176:179], v[120:123]
	v_mfma_f32_16x16x32_bf16 v[112:115], v[168:171], v[176:179], v[112:115]
	v_mfma_f32_16x16x32_bf16 v[104:107], v[160:163], v[194:197], v[104:107]
	v_mfma_f32_16x16x32_bf16 v[96:99], v[168:171], v[194:197], v[96:99]
	v_mfma_f32_16x16x32_bf16 v[88:91], v[160:163], v[202:205], v[88:91]
	v_mfma_f32_16x16x32_bf16 v[80:83], v[168:171], v[202:205], v[80:83]
	v_mfma_f32_16x16x32_bf16 v[72:75], v[160:163], v[210:213], v[72:75]
	v_mfma_f32_16x16x32_bf16 v[64:67], v[168:171], v[210:213], v[64:67]
	v_mfma_f32_16x16x32_bf16 v[120:123], v[164:167], v[180:183], v[120:123]
	v_mfma_f32_16x16x32_bf16 v[112:115], v[172:175], v[180:183], v[112:115]
	v_mfma_f32_16x16x32_bf16 v[104:107], v[164:167], v[198:201], v[104:107]
	v_mfma_f32_16x16x32_bf16 v[96:99], v[172:175], v[198:201], v[96:99]
	v_mfma_f32_16x16x32_bf16 v[88:91], v[164:167], v[206:209], v[88:91]
	v_mfma_f32_16x16x32_bf16 v[80:83], v[172:175], v[206:209], v[80:83]
	v_mfma_f32_16x16x32_bf16 v[72:75], v[164:167], v[214:217], v[72:75]
	v_mfma_f32_16x16x32_bf16 v[64:67], v[172:175], v[214:217], v[64:67]
	s_setprio 0
	s_barrier
	v_lshl_add_u64 v[138:139], s[60:61], 0, v[184:185]
	s_add_i32 s60, s70, s6
	s_mov_b32 m0, s60
	ds_read_b128 v[176:179], v146 offset:16384
	ds_read_b128 v[180:183], v146 offset:17408
	ds_read_b128 v[194:197], v146 offset:18432
	ds_read_b128 v[198:201], v146 offset:19456
	ds_read_b128 v[202:205], v146 offset:20480
	ds_read_b128 v[206:209], v146 offset:21504
	ds_read_b128 v[210:213], v146 offset:22528
	ds_read_b128 v[214:217], v146 offset:23552
	global_load_lds_dwordx4 v[138:139], off
	v_lshl_add_u64 v[218:219], v[138:139], 0, s[34:35]
	s_add_i32 m0, s60, 0x2000
	s_add_i32 s60, s84, s6
	global_load_lds_dwordx4 v[218:219], off
	v_lshl_add_u64 v[218:219], v[138:139], 0, s[92:93]
	s_mov_b32 m0, s60
	s_nop 0
	global_load_lds_dwordx4 v[218:219], off
	v_lshl_add_u64 v[218:219], v[138:139], 0, s[52:53]
	s_add_i32 m0, s60, 0x2000
	s_nop 0
	global_load_lds_dwordx4 v[218:219], off
	v_lshl_add_u64 v[218:219], s[14:15], 0, v[128:129]
	s_mov_b32 m0, s19
	v_lshl_add_u64 v[220:221], v[218:219], 0, s[34:35]
	global_load_lds_dwordx4 v[218:219], off
	s_mov_b32 m0, s20
	s_nop 0
	global_load_lds_dwordx4 v[220:221], off
	s_cmp_eq_u32 s98, 0
	s_cbranch_scc0 .Lrlx459_b
	s_waitcnt vmcnt(8)
.Lrlx459_b_back:
	s_waitcnt lgkmcnt(0)
	s_barrier
	s_setprio 1
	s_waitcnt lgkmcnt(0)
	v_mfma_f32_16x16x32_bf16 v[60:63], v[134:137], v[176:179], v[60:63]
	v_mfma_f32_16x16x32_bf16 v[52:55], v[152:155], v[176:179], v[52:55]
	v_mfma_f32_16x16x32_bf16 v[44:47], v[134:137], v[194:197], v[44:47]
	v_mfma_f32_16x16x32_bf16 v[36:39], v[152:155], v[194:197], v[36:39]
	v_mfma_f32_16x16x32_bf16 v[28:31], v[134:137], v[202:205], v[28:31]
	v_mfma_f32_16x16x32_bf16 v[20:23], v[152:155], v[202:205], v[20:23]
	v_mfma_f32_16x16x32_bf16 v[12:15], v[134:137], v[210:213], v[12:15]
	v_mfma_f32_16x16x32_bf16 v[4:7], v[152:155], v[210:213], v[4:7]
	v_mfma_f32_16x16x32_bf16 v[60:63], v[148:151], v[180:183], v[60:63]
	v_mfma_f32_16x16x32_bf16 v[52:55], v[156:159], v[180:183], v[52:55]
	v_mfma_f32_16x16x32_bf16 v[44:47], v[148:151], v[198:201], v[44:47]
	v_mfma_f32_16x16x32_bf16 v[36:39], v[156:159], v[198:201], v[36:39]
	v_mfma_f32_16x16x32_bf16 v[28:31], v[148:151], v[206:209], v[28:31]
	v_mfma_f32_16x16x32_bf16 v[20:23], v[156:159], v[206:209], v[20:23]
	v_mfma_f32_16x16x32_bf16 v[12:15], v[148:151], v[214:217], v[12:15]
	v_mfma_f32_16x16x32_bf16 v[4:7], v[156:159], v[214:217], v[4:7]
	s_setprio 0
	s_setprio 1
	v_mfma_f32_16x16x32_bf16 v[56:59], v[160:163], v[176:179], v[56:59]
	v_mfma_f32_16x16x32_bf16 v[48:51], v[168:171], v[176:179], v[48:51]
	v_mfma_f32_16x16x32_bf16 v[40:43], v[160:163], v[194:197], v[40:43]
	v_mfma_f32_16x16x32_bf16 v[32:35], v[168:171], v[194:197], v[32:35]
	v_mfma_f32_16x16x32_bf16 v[24:27], v[160:163], v[202:205], v[24:27]
	v_mfma_f32_16x16x32_bf16 v[16:19], v[168:171], v[202:205], v[16:19]
	v_mfma_f32_16x16x32_bf16 v[8:11], v[160:163], v[210:213], v[8:11]
	v_mfma_f32_16x16x32_bf16 v[0:3], v[168:171], v[210:213], v[0:3]
	v_mfma_f32_16x16x32_bf16 v[56:59], v[164:167], v[180:183], v[56:59]
	v_mfma_f32_16x16x32_bf16 v[48:51], v[172:175], v[180:183], v[48:51]
	v_mfma_f32_16x16x32_bf16 v[40:43], v[164:167], v[198:201], v[40:43]
	v_mfma_f32_16x16x32_bf16 v[32:35], v[172:175], v[198:201], v[32:35]
	v_mfma_f32_16x16x32_bf16 v[24:27], v[164:167], v[206:209], v[24:27]
	v_mfma_f32_16x16x32_bf16 v[16:19], v[172:175], v[206:209], v[16:19]
	v_mfma_f32_16x16x32_bf16 v[8:11], v[164:167], v[214:217], v[8:11]
	v_mfma_f32_16x16x32_bf16 v[0:3], v[172:175], v[214:217], v[0:3]
	s_setprio 0
	s_barrier
	s_add_i32 s14, 0, 0x18000
	v_add_u32_e32 v147, s14, v142
	s_add_i32 s15, 0, 0x1c000
	ds_read_b128 v[134:137], v147
	ds_read_b128 v[148:151], v147 offset:1024
	ds_read_b128 v[152:155], v147 offset:2048
	ds_read_b128 v[156:159], v147 offset:3072
	v_add_u32_e32 v147, s15, v142
	ds_read_b128 v[160:163], v147
	ds_read_b128 v[164:167], v147 offset:1024
	ds_read_b128 v[168:171], v147 offset:2048
	ds_read_b128 v[172:175], v147 offset:3072
	s_mov_b32 m0, s24
	v_lshl_add_u64 v[220:221], v[218:219], 0, s[92:93]
	ds_read_b128 v[176:179], v146 offset:32768
	ds_read_b128 v[180:183], v146 offset:33792
	ds_read_b128 v[194:197], v146 offset:34816
	ds_read_b128 v[198:201], v146 offset:35840
	ds_read_b128 v[202:205], v146 offset:36864
	ds_read_b128 v[206:209], v146 offset:37888
	ds_read_b128 v[210:213], v146 offset:38912
	ds_read_b128 v[214:217], v146 offset:39936
	global_load_lds_dwordx4 v[220:221], off
	v_lshl_add_u64 v[220:221], v[218:219], 0, s[52:53]
	s_mov_b32 m0, s25
	s_nop 0
	global_load_lds_dwordx4 v[220:221], off
	s_waitcnt vmcnt(8)
	s_waitcnt lgkmcnt(0)
	s_barrier
	s_setprio 1
	s_waitcnt lgkmcnt(0)
	v_mfma_f32_16x16x32_bf16 v[124:127], v[134:137], v[176:179], v[124:127]
	v_mfma_f32_16x16x32_bf16 v[116:119], v[152:155], v[176:179], v[116:119]
	v_mfma_f32_16x16x32_bf16 v[108:111], v[134:137], v[194:197], v[108:111]
	v_mfma_f32_16x16x32_bf16 v[100:103], v[152:155], v[194:197], v[100:103]
	v_mfma_f32_16x16x32_bf16 v[92:95], v[134:137], v[202:205], v[92:95]
	v_mfma_f32_16x16x32_bf16 v[84:87], v[152:155], v[202:205], v[84:87]
	v_mfma_f32_16x16x32_bf16 v[76:79], v[134:137], v[210:213], v[76:79]
	v_mfma_f32_16x16x32_bf16 v[68:71], v[152:155], v[210:213], v[68:71]
	v_mfma_f32_16x16x32_bf16 v[124:127], v[148:151], v[180:183], v[124:127]
	v_mfma_f32_16x16x32_bf16 v[116:119], v[156:159], v[180:183], v[116:119]
	v_mfma_f32_16x16x32_bf16 v[108:111], v[148:151], v[198:201], v[108:111]
	v_mfma_f32_16x16x32_bf16 v[100:103], v[156:159], v[198:201], v[100:103]
	v_mfma_f32_16x16x32_bf16 v[92:95], v[148:151], v[206:209], v[92:95]
	v_mfma_f32_16x16x32_bf16 v[84:87], v[156:159], v[206:209], v[84:87]
	v_mfma_f32_16x16x32_bf16 v[76:79], v[148:151], v[214:217], v[76:79]
	v_mfma_f32_16x16x32_bf16 v[68:71], v[156:159], v[214:217], v[68:71]
	s_setprio 0
	s_setprio 1
	v_mfma_f32_16x16x32_bf16 v[120:123], v[160:163], v[176:179], v[120:123]
	v_mfma_f32_16x16x32_bf16 v[112:115], v[168:171], v[176:179], v[112:115]
	v_mfma_f32_16x16x32_bf16 v[104:107], v[160:163], v[194:197], v[104:107]
	v_mfma_f32_16x16x32_bf16 v[96:99], v[168:171], v[194:197], v[96:99]
	v_mfma_f32_16x16x32_bf16 v[88:91], v[160:163], v[202:205], v[88:91]
	v_mfma_f32_16x16x32_bf16 v[80:83], v[168:171], v[202:205], v[80:83]
	v_mfma_f32_16x16x32_bf16 v[72:75], v[160:163], v[210:213], v[72:75]
	v_mfma_f32_16x16x32_bf16 v[64:67], v[168:171], v[210:213], v[64:67]
	v_mfma_f32_16x16x32_bf16 v[120:123], v[164:167], v[180:183], v[120:123]
	v_mfma_f32_16x16x32_bf16 v[112:115], v[172:175], v[180:183], v[112:115]
	v_mfma_f32_16x16x32_bf16 v[104:107], v[164:167], v[198:201], v[104:107]
	v_mfma_f32_16x16x32_bf16 v[96:99], v[172:175], v[198:201], v[96:99]
	v_mfma_f32_16x16x32_bf16 v[88:91], v[164:167], v[206:209], v[88:91]
	v_mfma_f32_16x16x32_bf16 v[80:83], v[172:175], v[206:209], v[80:83]
	v_mfma_f32_16x16x32_bf16 v[72:75], v[164:167], v[214:217], v[72:75]
	v_mfma_f32_16x16x32_bf16 v[64:67], v[172:175], v[214:217], v[64:67]
	s_setprio 0
	s_barrier
	s_add_i32 s14, s14, s6
	v_lshl_add_u64 v[220:221], v[138:139], 0, s[56:57]
	s_mov_b32 m0, s14
	ds_read_b128 v[176:179], v146 offset:49152
	ds_read_b128 v[180:183], v146 offset:50176
	ds_read_b128 v[194:197], v146 offset:51200
	ds_read_b128 v[198:201], v146 offset:52224
	ds_read_b128 v[202:205], v146 offset:53248
	ds_read_b128 v[206:209], v146 offset:54272
	ds_read_b128 v[210:213], v146 offset:55296
	ds_read_b128 v[214:217], v146 offset:56320
	global_load_lds_dwordx4 v[220:221], off
	v_lshl_add_u64 v[220:221], v[138:139], 0, s[96:97]
	s_add_i32 m0, s14, 0x2000
	s_add_i32 s14, s15, s6
	global_load_lds_dwordx4 v[220:221], off
	v_lshl_add_u64 v[220:221], v[138:139], 0, s[88:89]
	s_mov_b32 m0, s14
	v_lshl_add_u64 v[138:139], v[138:139], 0, s[68:69]
	global_load_lds_dwordx4 v[220:221], off
	s_add_i32 m0, s14, 0x2000
	s_nop 0
	global_load_lds_dwordx4 v[138:139], off
	v_lshl_add_u64 v[138:139], v[218:219], 0, s[56:57]
	s_mov_b32 m0, s26
	s_nop 0
	global_load_lds_dwordx4 v[138:139], off
	v_lshl_add_u64 v[138:139], v[218:219], 0, s[96:97]
	s_mov_b32 m0, s27
	s_nop 0
	global_load_lds_dwordx4 v[138:139], off
	s_waitcnt vmcnt(8)
	s_waitcnt lgkmcnt(0)
	s_barrier
	s_setprio 1
	s_waitcnt lgkmcnt(0)
	v_mfma_f32_16x16x32_bf16 v[60:63], v[134:137], v[176:179], v[60:63]
	v_mfma_f32_16x16x32_bf16 v[52:55], v[152:155], v[176:179], v[52:55]
	v_mfma_f32_16x16x32_bf16 v[44:47], v[134:137], v[194:197], v[44:47]
	v_mfma_f32_16x16x32_bf16 v[36:39], v[152:155], v[194:197], v[36:39]
	v_mfma_f32_16x16x32_bf16 v[28:31], v[134:137], v[202:205], v[28:31]
	v_mfma_f32_16x16x32_bf16 v[20:23], v[152:155], v[202:205], v[20:23]
	v_mfma_f32_16x16x32_bf16 v[12:15], v[134:137], v[210:213], v[12:15]
	v_mfma_f32_16x16x32_bf16 v[4:7], v[152:155], v[210:213], v[4:7]
	v_mfma_f32_16x16x32_bf16 v[60:63], v[148:151], v[180:183], v[60:63]
	v_mfma_f32_16x16x32_bf16 v[52:55], v[156:159], v[180:183], v[52:55]
	v_mfma_f32_16x16x32_bf16 v[44:47], v[148:151], v[198:201], v[44:47]
	v_mfma_f32_16x16x32_bf16 v[36:39], v[156:159], v[198:201], v[36:39]
	v_mfma_f32_16x16x32_bf16 v[28:31], v[148:151], v[206:209], v[28:31]
	v_mfma_f32_16x16x32_bf16 v[20:23], v[156:159], v[206:209], v[20:23]
	v_mfma_f32_16x16x32_bf16 v[12:15], v[148:151], v[214:217], v[12:15]
	v_mfma_f32_16x16x32_bf16 v[4:7], v[156:159], v[214:217], v[4:7]
	s_setprio 0
	s_setprio 1
	v_mfma_f32_16x16x32_bf16 v[56:59], v[160:163], v[176:179], v[56:59]
	v_mfma_f32_16x16x32_bf16 v[48:51], v[168:171], v[176:179], v[48:51]
	v_mfma_f32_16x16x32_bf16 v[40:43], v[160:163], v[194:197], v[40:43]
	v_mfma_f32_16x16x32_bf16 v[32:35], v[168:171], v[194:197], v[32:35]
	v_mfma_f32_16x16x32_bf16 v[24:27], v[160:163], v[202:205], v[24:27]
	v_mfma_f32_16x16x32_bf16 v[16:19], v[168:171], v[202:205], v[16:19]
	v_mfma_f32_16x16x32_bf16 v[8:11], v[160:163], v[210:213], v[8:11]
	v_mfma_f32_16x16x32_bf16 v[0:3], v[168:171], v[210:213], v[0:3]
	v_mfma_f32_16x16x32_bf16 v[56:59], v[164:167], v[180:183], v[56:59]
	v_mfma_f32_16x16x32_bf16 v[48:51], v[172:175], v[180:183], v[48:51]
	v_mfma_f32_16x16x32_bf16 v[40:43], v[164:167], v[198:201], v[40:43]
	v_mfma_f32_16x16x32_bf16 v[32:35], v[172:175], v[198:201], v[32:35]
	v_mfma_f32_16x16x32_bf16 v[24:27], v[164:167], v[206:209], v[24:27]
	v_mfma_f32_16x16x32_bf16 v[16:19], v[172:175], v[206:209], v[16:19]
	v_mfma_f32_16x16x32_bf16 v[8:11], v[164:167], v[214:217], v[8:11]
	v_mfma_f32_16x16x32_bf16 v[0:3], v[172:175], v[214:217], v[0:3]
	s_setprio 0
	s_barrier
	s_add_i32 s51, s51, 2
	s_add_u32 s48, s48, 0x100
	s_addc_u32 s49, s49, 0
	s_add_u32 s16, s16, 0x100
	s_addc_u32 s17, s17, 0
	s_cmp_gt_u32 s51, 13
	s_cbranch_scc0 .LBB0_459
	s_and_b64 vcc, exec, s[10:11]
	s_cbranch_vccz .LBB0_462
	s_barrier

.Lrlx459_a:
	s_waitcnt vmcnt(16)
	s_branch .Lrlx459_a_back
.Lrlx459_b:
	s_waitcnt vmcnt(16)
	s_mov_b32 s98, 0
	s_branch .Lrlx459_b_back

.LBB0_480:
	s_ashr_i32 s41, s40, 31
	s_lshl_b64 s[42:43], s[40:41], 19
	s_add_u32 s42, s64, s42
	s_addc_u32 s43, s65, s43
	s_and_b64 s[44:45], s[38:39], exec
	s_cselect_b32 s31, s43, s17
	s_cselect_b32 s41, s42, s16
	s_ashr_i32 s13, s12, 31
	s_lshl_b64 s[44:45], s[12:13], 19
	s_add_u32 s44, s22, s44
	s_addc_u32 s45, s23, s45
	s_and_b64 s[46:47], s[38:39], exec
	s_cselect_b32 s13, s45, s15
	s_cselect_b32 s48, s44, s14
	s_add_u32 s46, s16, 0x40080
	s_addc_u32 s47, s17, 0
	s_add_u32 s16, s14, 0x100
	v_mov_b32_e32 v0, 0
	s_addc_u32 s17, s15, 0
	s_mov_b32 s49, -2
	v_mov_b32_e32 v1, v0
	v_mov_b32_e32 v2, v0
	v_mov_b32_e32 v3, v0
	v_mov_b32_e32 v8, v0
	v_mov_b32_e32 v9, v0
	v_mov_b32_e32 v10, v0
	v_mov_b32_e32 v11, v0
	v_mov_b32_e32 v16, v0
	v_mov_b32_e32 v17, v0
	v_mov_b32_e32 v18, v0
	v_mov_b32_e32 v19, v0
	v_mov_b32_e32 v24, v0
	v_mov_b32_e32 v25, v0
	v_mov_b32_e32 v26, v0
	v_mov_b32_e32 v27, v0
	v_mov_b32_e32 v32, v0
	v_mov_b32_e32 v33, v0
	v_mov_b32_e32 v34, v0
	v_mov_b32_e32 v35, v0
	v_mov_b32_e32 v40, v0
	v_mov_b32_e32 v41, v0
	v_mov_b32_e32 v42, v0
	v_mov_b32_e32 v43, v0
	v_mov_b32_e32 v48, v0
	v_mov_b32_e32 v49, v0
	v_mov_b32_e32 v50, v0
	v_mov_b32_e32 v51, v0
	v_mov_b32_e32 v56, v0
	v_mov_b32_e32 v57, v0
	v_mov_b32_e32 v58, v0
	v_mov_b32_e32 v59, v0
	v_mov_b32_e32 v4, v0
	v_mov_b32_e32 v5, v0
	v_mov_b32_e32 v6, v0
	v_mov_b32_e32 v7, v0
	v_mov_b32_e32 v12, v0
	v_mov_b32_e32 v13, v0
	v_mov_b32_e32 v14, v0
	v_mov_b32_e32 v15, v0
	v_mov_b32_e32 v20, v0
	v_mov_b32_e32 v21, v0
	v_mov_b32_e32 v22, v0
	v_mov_b32_e32 v23, v0
	v_mov_b32_e32 v28, v0
	v_mov_b32_e32 v29, v0
	v_mov_b32_e32 v30, v0
	v_mov_b32_e32 v31, v0
	v_mov_b32_e32 v36, v0
	v_mov_b32_e32 v37, v0
	v_mov_b32_e32 v38, v0
	v_mov_b32_e32 v39, v0
	v_mov_b32_e32 v44, v0
	v_mov_b32_e32 v45, v0
	v_mov_b32_e32 v46, v0
	v_mov_b32_e32 v47, v0
	v_mov_b32_e32 v52, v0
	v_mov_b32_e32 v53, v0
	v_mov_b32_e32 v54, v0
	v_mov_b32_e32 v55, v0
	v_mov_b32_e32 v60, v0
	v_mov_b32_e32 v61, v0
	v_mov_b32_e32 v62, v0
	v_mov_b32_e32 v63, v0
	v_mov_b32_e32 v64, v0
	v_mov_b32_e32 v65, v0
	v_mov_b32_e32 v66, v0
	v_mov_b32_e32 v67, v0
	v_mov_b32_e32 v72, v0
	v_mov_b32_e32 v73, v0
	v_mov_b32_e32 v74, v0
	v_mov_b32_e32 v75, v0
	v_mov_b32_e32 v80, v0
	v_mov_b32_e32 v81, v0
	v_mov_b32_e32 v82, v0
	v_mov_b32_e32 v83, v0
	v_mov_b32_e32 v88, v0
	v_mov_b32_e32 v89, v0
	v_mov_b32_e32 v90, v0
	v_mov_b32_e32 v91, v0
	v_mov_b32_e32 v96, v0
	v_mov_b32_e32 v97, v0
	v_mov_b32_e32 v98, v0
	v_mov_b32_e32 v99, v0
	v_mov_b32_e32 v104, v0
	v_mov_b32_e32 v105, v0
	v_mov_b32_e32 v106, v0
	v_mov_b32_e32 v107, v0
	v_mov_b32_e32 v112, v0
	v_mov_b32_e32 v113, v0
	v_mov_b32_e32 v114, v0
	v_mov_b32_e32 v115, v0
	v_mov_b32_e32 v120, v0
	v_mov_b32_e32 v121, v0
	v_mov_b32_e32 v122, v0
	v_mov_b32_e32 v123, v0
	v_mov_b32_e32 v68, v0
	v_mov_b32_e32 v69, v0
	v_mov_b32_e32 v70, v0
	v_mov_b32_e32 v71, v0
	v_mov_b32_e32 v76, v0
	v_mov_b32_e32 v77, v0
	v_mov_b32_e32 v78, v0
	v_mov_b32_e32 v79, v0
	v_mov_b32_e32 v84, v0
	v_mov_b32_e32 v85, v0
	v_mov_b32_e32 v86, v0
	v_mov_b32_e32 v87, v0
	v_mov_b32_e32 v92, v0
	v_mov_b32_e32 v93, v0
	v_mov_b32_e32 v94, v0
	v_mov_b32_e32 v95, v0
	v_mov_b32_e32 v100, v0
	v_mov_b32_e32 v101, v0
	v_mov_b32_e32 v102, v0
	v_mov_b32_e32 v103, v0
	v_mov_b32_e32 v108, v0
	v_mov_b32_e32 v109, v0
	v_mov_b32_e32 v110, v0
	v_mov_b32_e32 v111, v0
	v_mov_b32_e32 v116, v0
	v_mov_b32_e32 v117, v0
	v_mov_b32_e32 v118, v0
	v_mov_b32_e32 v119, v0
	v_mov_b32_e32 v124, v0
	v_mov_b32_e32 v125, v0
	v_mov_b32_e32 v126, v0
	v_mov_b32_e32 v127, v0
	s_cmp_lg_u32 s28, 1
	s_cselect_b32 s98, 1, 0
.LBB0_481:
	s_add_u32 s14, s46, 0xfffc0080
	s_addc_u32 s15, s47, -1
	s_add_i32 s60, 0, 0x10000
	s_cmp_eq_u32 s49, 12
	s_cselect_b32 s15, s31, s15
	s_cselect_b32 s14, s41, s14
	v_add_u32_e32 v135, s60, v143
	s_cselect_b32 s51, s13, s17
	s_cselect_b32 s50, s48, s16
	s_add_i32 s61, 0, 0x14000
	ds_read_b128 v[136:139], v135
	ds_read_b128 v[148:151], v135 offset:1024
	ds_read_b128 v[152:155], v135 offset:2048
	ds_read_b128 v[156:159], v135 offset:3072
	v_add_u32_e32 v135, s61, v143
	ds_read_b128 v[160:163], v135
	ds_read_b128 v[164:167], v135 offset:1024
	ds_read_b128 v[168:171], v135 offset:2048
	ds_read_b128 v[172:175], v135 offset:3072
	v_lshl_add_u64 v[140:141], s[46:47], 0, v[184:185]
	s_add_i32 m0, s19, 0xc000
	ds_read_b128 v[176:179], v147
	ds_read_b128 v[180:183], v147 offset:1024
	ds_read_b128 v[194:197], v147 offset:2048
	ds_read_b128 v[198:201], v147 offset:3072
	ds_read_b128 v[202:205], v147 offset:4096
	ds_read_b128 v[206:209], v147 offset:5120
	ds_read_b128 v[210:213], v147 offset:6144
	ds_read_b128 v[214:217], v147 offset:7168
	global_load_lds_dwordx4 v[140:141], off
	v_lshl_add_u64 v[140:141], v[140:141], 0, s[34:35]
	s_add_i32 m0, s19, 0xe000
	s_nop 0
	global_load_lds_dwordx4 v[140:141], off
	s_cmp_eq_u32 s98, 0
	s_cbranch_scc0 .Lrlx481_a
	s_waitcnt vmcnt(8)
.Lrlx481_a_back:
	s_waitcnt lgkmcnt(0)
	s_barrier
	s_setprio 1
	s_waitcnt lgkmcnt(0)
	v_mfma_f32_16x16x32_bf16 v[124:127], v[136:139], v[176:179], v[124:127]
	v_mfma_f32_16x16x32_bf16 v[116:119], v[152:155], v[176:179], v[116:119]
	v_mfma_f32_16x16x32_bf16 v[108:111], v[136:139], v[194:197], v[108:111]
	v_mfma_f32_16x16x32_bf16 v[100:103], v[152:155], v[194:197], v[100:103]
	v_mfma_f32_16x16x32_bf16 v[92:95], v[136:139], v[202:205], v[92:95]
	v_mfma_f32_16x16x32_bf16 v[84:87], v[152:155], v[202:205], v[84:87]
	v_mfma_f32_16x16x32_bf16 v[76:79], v[136:139], v[210:213], v[76:79]
	v_mfma_f32_16x16x32_bf16 v[68:71], v[152:155], v[210:213], v[68:71]
	v_mfma_f32_16x16x32_bf16 v[124:127], v[148:151], v[180:183], v[124:127]
	v_mfma_f32_16x16x32_bf16 v[116:119], v[156:159], v[180:183], v[116:119]
	v_mfma_f32_16x16x32_bf16 v[108:111], v[148:151], v[198:201], v[108:111]
	v_mfma_f32_16x16x32_bf16 v[100:103], v[156:159], v[198:201], v[100:103]
	v_mfma_f32_16x16x32_bf16 v[92:95], v[148:151], v[206:209], v[92:95]
	v_mfma_f32_16x16x32_bf16 v[84:87], v[156:159], v[206:209], v[84:87]
	v_mfma_f32_16x16x32_bf16 v[76:79], v[148:151], v[214:217], v[76:79]
	v_mfma_f32_16x16x32_bf16 v[68:71], v[156:159], v[214:217], v[68:71]
	s_setprio 0
	s_setprio 1
	v_mfma_f32_16x16x32_bf16 v[120:123], v[160:163], v[176:179], v[120:123]
	v_mfma_f32_16x16x32_bf16 v[112:115], v[168:171], v[176:179], v[112:115]
	v_mfma_f32_16x16x32_bf16 v[104:107], v[160:163], v[194:197], v[104:107]
	v_mfma_f32_16x16x32_bf16 v[96:99], v[168:171], v[194:197], v[96:99]
	v_mfma_f32_16x16x32_bf16 v[88:91], v[160:163], v[202:205], v[88:91]
	v_mfma_f32_16x16x32_bf16 v[80:83], v[168:171], v[202:205], v[80:83]
	v_mfma_f32_16x16x32_bf16 v[72:75], v[160:163], v[210:213], v[72:75]
	v_mfma_f32_16x16x32_bf16 v[64:67], v[168:171], v[210:213], v[64:67]
	v_mfma_f32_16x16x32_bf16 v[120:123], v[164:167], v[180:183], v[120:123]
	v_mfma_f32_16x16x32_bf16 v[112:115], v[172:175], v[180:183], v[112:115]
	v_mfma_f32_16x16x32_bf16 v[104:107], v[164:167], v[198:201], v[104:107]
	v_mfma_f32_16x16x32_bf16 v[96:99], v[172:175], v[198:201], v[96:99]
	v_mfma_f32_16x16x32_bf16 v[88:91], v[164:167], v[206:209], v[88:91]
	v_mfma_f32_16x16x32_bf16 v[80:83], v[172:175], v[206:209], v[80:83]
	v_mfma_f32_16x16x32_bf16 v[72:75], v[164:167], v[214:217], v[72:75]
	v_mfma_f32_16x16x32_bf16 v[64:67], v[172:175], v[214:217], v[64:67]
	s_setprio 0
	s_barrier
	v_lshl_add_u64 v[140:141], s[50:51], 0, v[128:129]
	s_add_i32 s50, s60, s6
	s_mov_b32 m0, s50
	ds_read_b128 v[176:179], v147 offset:16384
	ds_read_b128 v[180:183], v147 offset:17408
	ds_read_b128 v[194:197], v147 offset:18432
	ds_read_b128 v[198:201], v147 offset:19456
	ds_read_b128 v[202:205], v147 offset:20480
	ds_read_b128 v[206:209], v147 offset:21504
	ds_read_b128 v[210:213], v147 offset:22528
	ds_read_b128 v[214:217], v147 offset:23552
	global_load_lds_dwordx4 v[140:141], off
	v_lshl_add_u64 v[218:219], v[140:141], 0, s[34:35]
	s_add_i32 m0, s50, 0x2000
	s_add_i32 s50, s61, s6
	global_load_lds_dwordx4 v[218:219], off
	v_lshl_add_u64 v[218:219], v[140:141], 0, s[92:93]
	s_mov_b32 m0, s50
	s_nop 0
	global_load_lds_dwordx4 v[218:219], off
	v_lshl_add_u64 v[218:219], v[140:141], 0, s[52:53]
	s_add_i32 m0, s50, 0x2000
	s_nop 0
	global_load_lds_dwordx4 v[218:219], off
	v_lshl_add_u64 v[218:219], s[14:15], 0, v[130:131]
	s_mov_b32 m0, s19
	v_lshl_add_u64 v[220:221], v[218:219], 0, s[34:35]
	global_load_lds_dwordx4 v[218:219], off
	s_mov_b32 m0, s20
	s_nop 0
	global_load_lds_dwordx4 v[220:221], off
	s_cmp_eq_u32 s98, 0
	s_cbranch_scc0 .Lrlx481_b
	s_waitcnt vmcnt(8)
.Lrlx481_b_back:
	s_waitcnt lgkmcnt(0)
	s_barrier
	s_setprio 1
	s_waitcnt lgkmcnt(0)
	v_mfma_f32_16x16x32_bf16 v[60:63], v[136:139], v[176:179], v[60:63]
	v_mfma_f32_16x16x32_bf16 v[52:55], v[152:155], v[176:179], v[52:55]
	v_mfma_f32_16x16x32_bf16 v[44:47], v[136:139], v[194:197], v[44:47]
	v_mfma_f32_16x16x32_bf16 v[36:39], v[152:155], v[194:197], v[36:39]
	v_mfma_f32_16x16x32_bf16 v[28:31], v[136:139], v[202:205], v[28:31]
	v_mfma_f32_16x16x32_bf16 v[20:23], v[152:155], v[202:205], v[20:23]
	v_mfma_f32_16x16x32_bf16 v[12:15], v[136:139], v[210:213], v[12:15]
	v_mfma_f32_16x16x32_bf16 v[4:7], v[152:155], v[210:213], v[4:7]
	v_mfma_f32_16x16x32_bf16 v[60:63], v[148:151], v[180:183], v[60:63]
	v_mfma_f32_16x16x32_bf16 v[52:55], v[156:159], v[180:183], v[52:55]
	v_mfma_f32_16x16x32_bf16 v[44:47], v[148:151], v[198:201], v[44:47]
	v_mfma_f32_16x16x32_bf16 v[36:39], v[156:159], v[198:201], v[36:39]
	v_mfma_f32_16x16x32_bf16 v[28:31], v[148:151], v[206:209], v[28:31]
	v_mfma_f32_16x16x32_bf16 v[20:23], v[156:159], v[206:209], v[20:23]
	v_mfma_f32_16x16x32_bf16 v[12:15], v[148:151], v[214:217], v[12:15]
	v_mfma_f32_16x16x32_bf16 v[4:7], v[156:159], v[214:217], v[4:7]
	s_setprio 0
	s_setprio 1
	v_mfma_f32_16x16x32_bf16 v[56:59], v[160:163], v[176:179], v[56:59]
	v_mfma_f32_16x16x32_bf16 v[48:51], v[168:171], v[176:179], v[48:51]
	v_mfma_f32_16x16x32_bf16 v[40:43], v[160:163], v[194:197], v[40:43]
	v_mfma_f32_16x16x32_bf16 v[32:35], v[168:171], v[194:197], v[32:35]
	v_mfma_f32_16x16x32_bf16 v[24:27], v[160:163], v[202:205], v[24:27]
	v_mfma_f32_16x16x32_bf16 v[16:19], v[168:171], v[202:205], v[16:19]
	v_mfma_f32_16x16x32_bf16 v[8:11], v[160:163], v[210:213], v[8:11]
	v_mfma_f32_16x16x32_bf16 v[0:3], v[168:171], v[210:213], v[0:3]
	v_mfma_f32_16x16x32_bf16 v[56:59], v[164:167], v[180:183], v[56:59]
	v_mfma_f32_16x16x32_bf16 v[48:51], v[172:175], v[180:183], v[48:51]
	v_mfma_f32_16x16x32_bf16 v[40:43], v[164:167], v[198:201], v[40:43]
	v_mfma_f32_16x16x32_bf16 v[32:35], v[172:175], v[198:201], v[32:35]
	v_mfma_f32_16x16x32_bf16 v[24:27], v[164:167], v[206:209], v[24:27]
	v_mfma_f32_16x16x32_bf16 v[16:19], v[172:175], v[206:209], v[16:19]
	v_mfma_f32_16x16x32_bf16 v[8:11], v[164:167], v[214:217], v[8:11]
	v_mfma_f32_16x16x32_bf16 v[0:3], v[172:175], v[214:217], v[0:3]
	s_setprio 0
	s_barrier
	s_add_i32 s14, 0, 0x18000
	v_add_u32_e32 v135, s14, v143
	s_add_i32 s15, 0, 0x1c000
	ds_read_b128 v[136:139], v135
	ds_read_b128 v[148:151], v135 offset:1024
	ds_read_b128 v[152:155], v135 offset:2048
	ds_read_b128 v[156:159], v135 offset:3072
	v_add_u32_e32 v135, s15, v143
	ds_read_b128 v[160:163], v135
	ds_read_b128 v[164:167], v135 offset:1024
	ds_read_b128 v[168:171], v135 offset:2048
	ds_read_b128 v[172:175], v135 offset:3072
	s_mov_b32 m0, s24
	v_lshl_add_u64 v[220:221], v[218:219], 0, s[92:93]
	ds_read_b128 v[176:179], v147 offset:32768
	ds_read_b128 v[180:183], v147 offset:33792
	ds_read_b128 v[194:197], v147 offset:34816
	ds_read_b128 v[198:201], v147 offset:35840
	ds_read_b128 v[202:205], v147 offset:36864
	ds_read_b128 v[206:209], v147 offset:37888
	ds_read_b128 v[210:213], v147 offset:38912
	ds_read_b128 v[214:217], v147 offset:39936
	global_load_lds_dwordx4 v[220:221], off
	v_lshl_add_u64 v[220:221], v[218:219], 0, s[52:53]
	s_mov_b32 m0, s25
	s_nop 0
	global_load_lds_dwordx4 v[220:221], off
	s_waitcnt vmcnt(8)
	s_waitcnt lgkmcnt(0)
	s_barrier
	s_setprio 1
	s_waitcnt lgkmcnt(0)
	v_mfma_f32_16x16x32_bf16 v[124:127], v[136:139], v[176:179], v[124:127]
	v_mfma_f32_16x16x32_bf16 v[116:119], v[152:155], v[176:179], v[116:119]
	v_mfma_f32_16x16x32_bf16 v[108:111], v[136:139], v[194:197], v[108:111]
	v_mfma_f32_16x16x32_bf16 v[100:103], v[152:155], v[194:197], v[100:103]
	v_mfma_f32_16x16x32_bf16 v[92:95], v[136:139], v[202:205], v[92:95]
	v_mfma_f32_16x16x32_bf16 v[84:87], v[152:155], v[202:205], v[84:87]
	v_mfma_f32_16x16x32_bf16 v[76:79], v[136:139], v[210:213], v[76:79]
	v_mfma_f32_16x16x32_bf16 v[68:71], v[152:155], v[210:213], v[68:71]
	v_mfma_f32_16x16x32_bf16 v[124:127], v[148:151], v[180:183], v[124:127]
	v_mfma_f32_16x16x32_bf16 v[116:119], v[156:159], v[180:183], v[116:119]
	v_mfma_f32_16x16x32_bf16 v[108:111], v[148:151], v[198:201], v[108:111]
	v_mfma_f32_16x16x32_bf16 v[100:103], v[156:159], v[198:201], v[100:103]
	v_mfma_f32_16x16x32_bf16 v[92:95], v[148:151], v[206:209], v[92:95]
	v_mfma_f32_16x16x32_bf16 v[84:87], v[156:159], v[206:209], v[84:87]
	v_mfma_f32_16x16x32_bf16 v[76:79], v[148:151], v[214:217], v[76:79]
	v_mfma_f32_16x16x32_bf16 v[68:71], v[156:159], v[214:217], v[68:71]
	s_setprio 0
	s_setprio 1
	v_mfma_f32_16x16x32_bf16 v[120:123], v[160:163], v[176:179], v[120:123]
	v_mfma_f32_16x16x32_bf16 v[112:115], v[168:171], v[176:179], v[112:115]
	v_mfma_f32_16x16x32_bf16 v[104:107], v[160:163], v[194:197], v[104:107]
	v_mfma_f32_16x16x32_bf16 v[96:99], v[168:171], v[194:197], v[96:99]
	v_mfma_f32_16x16x32_bf16 v[88:91], v[160:163], v[202:205], v[88:91]
	v_mfma_f32_16x16x32_bf16 v[80:83], v[168:171], v[202:205], v[80:83]
	v_mfma_f32_16x16x32_bf16 v[72:75], v[160:163], v[210:213], v[72:75]
	v_mfma_f32_16x16x32_bf16 v[64:67], v[168:171], v[210:213], v[64:67]
	v_mfma_f32_16x16x32_bf16 v[120:123], v[164:167], v[180:183], v[120:123]
	v_mfma_f32_16x16x32_bf16 v[112:115], v[172:175], v[180:183], v[112:115]
	v_mfma_f32_16x16x32_bf16 v[104:107], v[164:167], v[198:201], v[104:107]
	v_mfma_f32_16x16x32_bf16 v[96:99], v[172:175], v[198:201], v[96:99]
	v_mfma_f32_16x16x32_bf16 v[88:91], v[164:167], v[206:209], v[88:91]
	v_mfma_f32_16x16x32_bf16 v[80:83], v[172:175], v[206:209], v[80:83]
	v_mfma_f32_16x16x32_bf16 v[72:75], v[164:167], v[214:217], v[72:75]
	v_mfma_f32_16x16x32_bf16 v[64:67], v[172:175], v[214:217], v[64:67]
	s_setprio 0
	s_barrier
	s_add_i32 s14, s14, s6
	v_lshl_add_u64 v[220:221], v[140:141], 0, s[56:57]
	s_mov_b32 m0, s14
	ds_read_b128 v[176:179], v147 offset:49152
	ds_read_b128 v[180:183], v147 offset:50176
	ds_read_b128 v[194:197], v147 offset:51200
	ds_read_b128 v[198:201], v147 offset:52224
	ds_read_b128 v[202:205], v147 offset:53248
	ds_read_b128 v[206:209], v147 offset:54272
	ds_read_b128 v[210:213], v147 offset:55296
	ds_read_b128 v[214:217], v147 offset:56320
	global_load_lds_dwordx4 v[220:221], off
	v_lshl_add_u64 v[220:221], v[140:141], 0, s[96:97]
	s_add_i32 m0, s14, 0x2000
	s_add_i32 s14, s15, s6
	global_load_lds_dwordx4 v[220:221], off
	v_lshl_add_u64 v[220:221], v[140:141], 0, s[88:89]
	s_mov_b32 m0, s14
	v_lshl_add_u64 v[140:141], v[140:141], 0, s[68:69]
	global_load_lds_dwordx4 v[220:221], off
	s_add_i32 m0, s14, 0x2000
	s_nop 0
	global_load_lds_dwordx4 v[140:141], off
	v_lshl_add_u64 v[140:141], v[218:219], 0, s[56:57]
	s_mov_b32 m0, s26
	s_nop 0
	global_load_lds_dwordx4 v[140:141], off
	v_lshl_add_u64 v[140:141], v[218:219], 0, s[96:97]
	s_mov_b32 m0, s27
	s_nop 0
	global_load_lds_dwordx4 v[140:141], off
	s_waitcnt vmcnt(8)
	s_waitcnt lgkmcnt(0)
	s_barrier
	s_setprio 1
	s_waitcnt lgkmcnt(0)
	v_mfma_f32_16x16x32_bf16 v[60:63], v[136:139], v[176:179], v[60:63]
	v_mfma_f32_16x16x32_bf16 v[52:55], v[152:155], v[176:179], v[52:55]
	v_mfma_f32_16x16x32_bf16 v[44:47], v[136:139], v[194:197], v[44:47]
	v_mfma_f32_16x16x32_bf16 v[36:39], v[152:155], v[194:197], v[36:39]
	v_mfma_f32_16x16x32_bf16 v[28:31], v[136:139], v[202:205], v[28:31]
	v_mfma_f32_16x16x32_bf16 v[20:23], v[152:155], v[202:205], v[20:23]
	v_mfma_f32_16x16x32_bf16 v[12:15], v[136:139], v[210:213], v[12:15]
	v_mfma_f32_16x16x32_bf16 v[4:7], v[152:155], v[210:213], v[4:7]
	v_mfma_f32_16x16x32_bf16 v[60:63], v[148:151], v[180:183], v[60:63]
	v_mfma_f32_16x16x32_bf16 v[52:55], v[156:159], v[180:183], v[52:55]
	v_mfma_f32_16x16x32_bf16 v[44:47], v[148:151], v[198:201], v[44:47]
	v_mfma_f32_16x16x32_bf16 v[36:39], v[156:159], v[198:201], v[36:39]
	v_mfma_f32_16x16x32_bf16 v[28:31], v[148:151], v[206:209], v[28:31]
	v_mfma_f32_16x16x32_bf16 v[20:23], v[156:159], v[206:209], v[20:23]
	v_mfma_f32_16x16x32_bf16 v[12:15], v[148:151], v[214:217], v[12:15]
	v_mfma_f32_16x16x32_bf16 v[4:7], v[156:159], v[214:217], v[4:7]
	s_setprio 0
	s_setprio 1
	v_mfma_f32_16x16x32_bf16 v[56:59], v[160:163], v[176:179], v[56:59]
	v_mfma_f32_16x16x32_bf16 v[48:51], v[168:171], v[176:179], v[48:51]
	v_mfma_f32_16x16x32_bf16 v[40:43], v[160:163], v[194:197], v[40:43]
	v_mfma_f32_16x16x32_bf16 v[32:35], v[168:171], v[194:197], v[32:35]
	v_mfma_f32_16x16x32_bf16 v[24:27], v[160:163], v[202:205], v[24:27]
	v_mfma_f32_16x16x32_bf16 v[16:19], v[168:171], v[202:205], v[16:19]
	v_mfma_f32_16x16x32_bf16 v[8:11], v[160:163], v[210:213], v[8:11]
	v_mfma_f32_16x16x32_bf16 v[0:3], v[168:171], v[210:213], v[0:3]
	v_mfma_f32_16x16x32_bf16 v[56:59], v[164:167], v[180:183], v[56:59]
	v_mfma_f32_16x16x32_bf16 v[48:51], v[172:175], v[180:183], v[48:51]
	v_mfma_f32_16x16x32_bf16 v[40:43], v[164:167], v[198:201], v[40:43]
	v_mfma_f32_16x16x32_bf16 v[32:35], v[172:175], v[198:201], v[32:35]
	v_mfma_f32_16x16x32_bf16 v[24:27], v[164:167], v[206:209], v[24:27]
	v_mfma_f32_16x16x32_bf16 v[16:19], v[172:175], v[206:209], v[16:19]
	v_mfma_f32_16x16x32_bf16 v[8:11], v[164:167], v[214:217], v[8:11]
	v_mfma_f32_16x16x32_bf16 v[0:3], v[172:175], v[214:217], v[0:3]
	s_setprio 0
	s_barrier
	s_add_i32 s49, s49, 2
	s_add_u32 s46, s46, 0x100
	s_addc_u32 s47, s47, 0
	s_add_u32 s16, s16, 0x100
	s_addc_u32 s17, s17, 0
	s_cmp_gt_u32 s49, 13
	s_cbranch_scc0 .LBB0_481
	s_and_b64 vcc, exec, s[10:11]
	s_cbranch_vccz .LBB0_484
	s_barrier

.LBB0_502:
	s_ashr_i32 s13, s12, 31
	s_lshl_b64 s[42:43], s[12:13], 18
	s_add_u32 s42, s54, s42
	s_addc_u32 s43, s55, s43
	s_and_b64 s[44:45], s[40:41], exec
	s_cselect_b32 s13, s43, s17
	s_cselect_b32 s31, s42, s16
	s_ashr_i32 s11, s10, 31
	s_lshl_b64 s[44:45], s[10:11], 18
	s_add_u32 s44, s22, s44
	s_addc_u32 s45, s23, s45
	s_and_b64 s[46:47], s[40:41], exec
	s_cselect_b32 s11, s45, s15
	s_cselect_b32 s48, s44, s14
	s_add_u32 s46, s16, 0x20080
	s_addc_u32 s47, s17, 0
	s_add_u32 s49, s14, 0x100
	v_mov_b32_e32 v32, 0
	s_addc_u32 s50, s15, 0
	s_mov_b32 s51, -2
	v_mov_b32_e32 v33, v32
	v_mov_b32_e32 v34, v32
	v_mov_b32_e32 v35, v32
	v_mov_b32_e32 v40, v32
	v_mov_b32_e32 v41, v32
	v_mov_b32_e32 v42, v32
	v_mov_b32_e32 v43, v32
	v_mov_b32_e32 v48, v32
	v_mov_b32_e32 v49, v32
	v_mov_b32_e32 v50, v32
	v_mov_b32_e32 v51, v32
	v_mov_b32_e32 v56, v32
	v_mov_b32_e32 v57, v32
	v_mov_b32_e32 v58, v32
	v_mov_b32_e32 v59, v32
	v_mov_b32_e32 v64, v32
	v_mov_b32_e32 v65, v32
	v_mov_b32_e32 v66, v32
	v_mov_b32_e32 v67, v32
	v_mov_b32_e32 v72, v32
	v_mov_b32_e32 v73, v32
	v_mov_b32_e32 v74, v32
	v_mov_b32_e32 v75, v32
	v_mov_b32_e32 v80, v32
	v_mov_b32_e32 v81, v32
	v_mov_b32_e32 v82, v32
	v_mov_b32_e32 v83, v32
	v_mov_b32_e32 v88, v32
	v_mov_b32_e32 v89, v32
	v_mov_b32_e32 v90, v32
	v_mov_b32_e32 v91, v32
	v_mov_b32_e32 v36, v32
	v_mov_b32_e32 v37, v32
	v_mov_b32_e32 v38, v32
	v_mov_b32_e32 v39, v32
	v_mov_b32_e32 v44, v32
	v_mov_b32_e32 v45, v32
	v_mov_b32_e32 v46, v32
	v_mov_b32_e32 v47, v32
	v_mov_b32_e32 v52, v32
	v_mov_b32_e32 v53, v32
	v_mov_b32_e32 v54, v32
	v_mov_b32_e32 v55, v32
	v_mov_b32_e32 v60, v32
	v_mov_b32_e32 v61, v32
	v_mov_b32_e32 v62, v32
	v_mov_b32_e32 v63, v32
	v_mov_b32_e32 v68, v32
	v_mov_b32_e32 v69, v32
	v_mov_b32_e32 v70, v32
	v_mov_b32_e32 v71, v32
	v_mov_b32_e32 v76, v32
	v_mov_b32_e32 v77, v32
	v_mov_b32_e32 v78, v32
	v_mov_b32_e32 v79, v32
	v_mov_b32_e32 v84, v32
	v_mov_b32_e32 v85, v32
	v_mov_b32_e32 v86, v32
	v_mov_b32_e32 v87, v32
	v_mov_b32_e32 v92, v32
	v_mov_b32_e32 v93, v32
	v_mov_b32_e32 v94, v32
	v_mov_b32_e32 v95, v32
	v_mov_b32_e32 v96, v32
	v_mov_b32_e32 v97, v32
	v_mov_b32_e32 v98, v32
	v_mov_b32_e32 v99, v32
	v_mov_b32_e32 v104, v32
	v_mov_b32_e32 v105, v32
	v_mov_b32_e32 v106, v32
	v_mov_b32_e32 v107, v32
	v_mov_b32_e32 v112, v32
	v_mov_b32_e32 v113, v32
	v_mov_b32_e32 v114, v32
	v_mov_b32_e32 v115, v32
	v_mov_b32_e32 v120, v32
	v_mov_b32_e32 v121, v32
	v_mov_b32_e32 v122, v32
	v_mov_b32_e32 v123, v32
	v_mov_b32_e32 v128, v32
	v_mov_b32_e32 v129, v32
	v_mov_b32_e32 v130, v32
	v_mov_b32_e32 v131, v32
	v_mov_b32_e32 v136, v32
	v_mov_b32_e32 v137, v32
	v_mov_b32_e32 v138, v32
	v_mov_b32_e32 v139, v32
	v_mov_b32_e32 v144, v32
	v_mov_b32_e32 v145, v32
	v_mov_b32_e32 v146, v32
	v_mov_b32_e32 v147, v32
	v_mov_b32_e32 v152, v32
	v_mov_b32_e32 v153, v32
	v_mov_b32_e32 v154, v32
	v_mov_b32_e32 v155, v32
	v_mov_b32_e32 v100, v32
	v_mov_b32_e32 v101, v32
	v_mov_b32_e32 v102, v32
	v_mov_b32_e32 v103, v32
	v_mov_b32_e32 v108, v32
	v_mov_b32_e32 v109, v32
	v_mov_b32_e32 v110, v32
	v_mov_b32_e32 v111, v32
	v_mov_b32_e32 v116, v32
	v_mov_b32_e32 v117, v32
	v_mov_b32_e32 v118, v32
	v_mov_b32_e32 v119, v32
	v_mov_b32_e32 v124, v32
	v_mov_b32_e32 v125, v32
	v_mov_b32_e32 v126, v32
	v_mov_b32_e32 v127, v32
	v_mov_b32_e32 v132, v32
	v_mov_b32_e32 v133, v32
	v_mov_b32_e32 v134, v32
	v_mov_b32_e32 v135, v32
	v_mov_b32_e32 v140, v32
	v_mov_b32_e32 v141, v32
	v_mov_b32_e32 v142, v32
	v_mov_b32_e32 v143, v32
	v_mov_b32_e32 v148, v32
	v_mov_b32_e32 v149, v32
	v_mov_b32_e32 v150, v32
	v_mov_b32_e32 v151, v32
	v_mov_b32_e32 v156, v32
	v_mov_b32_e32 v157, v32
	v_mov_b32_e32 v158, v32
	v_mov_b32_e32 v159, v32
	s_cmp_lg_u32 s28, 1
	s_cselect_b32 s98, 1, 0
.LBB0_503:
	s_add_u32 s14, s46, 0xfffe0080
	s_addc_u32 s15, s47, -1
	s_add_i32 s60, 0, 0x10000
	s_cmp_eq_u32 s51, 4
	s_cselect_b32 s15, s13, s15
	s_cselect_b32 s14, s31, s14
	s_cselect_b32 s17, s11, s50
	s_cselect_b32 s16, s48, s49
	s_add_i32 s61, 0, 0x14000
	v_add_u32_e32 v0, s60, v172
	v_add_u32_e32 v4, s61, v172
	ds_read_b128 v[24:27], v0
	ds_read_b128 v[28:31], v0 offset:1024
	ds_read_b128 v[16:19], v0 offset:2048
	ds_read_b128 v[20:23], v0 offset:3072
	ds_read_b128 v[8:11], v4
	ds_read_b128 v[12:15], v4 offset:1024
	ds_read_b128 v[0:3], v4 offset:2048
	ds_read_b128 v[4:7], v4 offset:3072
	v_lshl_add_u64 v[166:167], s[46:47], 0, v[164:165]
	s_add_i32 m0, s19, 0xc000
	ds_read_b128 v[194:197], v176
	ds_read_b128 v[198:201], v176 offset:1024
	ds_read_b128 v[202:205], v176 offset:2048
	ds_read_b128 v[206:209], v176 offset:3072
	ds_read_b128 v[210:213], v176 offset:4096
	ds_read_b128 v[214:217], v176 offset:5120
	ds_read_b128 v[218:221], v176 offset:6144
	ds_read_b128 v[222:225], v176 offset:7168
	global_load_lds_dwordx4 v[166:167], off
	v_lshl_add_u64 v[166:167], v[166:167], 0, s[94:95]
	s_add_i32 m0, s19, 0xe000
	s_nop 0
	global_load_lds_dwordx4 v[166:167], off
	s_cmp_eq_u32 s98, 0
	s_cbranch_scc0 .Lrlx503_a
	s_waitcnt vmcnt(8)
.Lrlx503_a_back:
	s_waitcnt lgkmcnt(0)
	s_barrier
	s_setprio 1
	s_waitcnt lgkmcnt(0)
	v_mfma_scale_f32_16x16x128_f8f6f4 v[156:159], v[24:31], v[194:201], v[156:159], v240, v240 op_sel_hi:[0,0,0]
	v_mfma_scale_f32_16x16x128_f8f6f4 v[148:151], v[16:23], v[194:201], v[148:151], v240, v240 op_sel_hi:[0,0,0]
	v_mfma_scale_f32_16x16x128_f8f6f4 v[140:143], v[24:31], v[202:209], v[140:143], v240, v240 op_sel_hi:[0,0,0]
	v_mfma_scale_f32_16x16x128_f8f6f4 v[132:135], v[16:23], v[202:209], v[132:135], v240, v240 op_sel_hi:[0,0,0]
	v_mfma_scale_f32_16x16x128_f8f6f4 v[124:127], v[24:31], v[210:217], v[124:127], v240, v240 op_sel_hi:[0,0,0]
	v_mfma_scale_f32_16x16x128_f8f6f4 v[116:119], v[16:23], v[210:217], v[116:119], v240, v240 op_sel_hi:[0,0,0]
	v_mfma_scale_f32_16x16x128_f8f6f4 v[108:111], v[24:31], v[218:225], v[108:111], v240, v240 op_sel_hi:[0,0,0]
	v_mfma_scale_f32_16x16x128_f8f6f4 v[100:103], v[16:23], v[218:225], v[100:103], v240, v240 op_sel_hi:[0,0,0]
	s_setprio 0
	s_setprio 1
	v_mfma_scale_f32_16x16x128_f8f6f4 v[152:155], v[8:15], v[194:201], v[152:155], v240, v240 op_sel_hi:[0,0,0]
	v_mfma_scale_f32_16x16x128_f8f6f4 v[144:147], v[0:7], v[194:201], v[144:147], v240, v240 op_sel_hi:[0,0,0]
	v_mfma_scale_f32_16x16x128_f8f6f4 v[136:139], v[8:15], v[202:209], v[136:139], v240, v240 op_sel_hi:[0,0,0]
	v_mfma_scale_f32_16x16x128_f8f6f4 v[128:131], v[0:7], v[202:209], v[128:131], v240, v240 op_sel_hi:[0,0,0]
	v_mfma_scale_f32_16x16x128_f8f6f4 v[120:123], v[8:15], v[210:217], v[120:123], v240, v240 op_sel_hi:[0,0,0]
	v_mfma_scale_f32_16x16x128_f8f6f4 v[112:115], v[0:7], v[210:217], v[112:115], v240, v240 op_sel_hi:[0,0,0]
	v_mfma_scale_f32_16x16x128_f8f6f4 v[104:107], v[8:15], v[218:225], v[104:107], v240, v240 op_sel_hi:[0,0,0]
	v_mfma_scale_f32_16x16x128_f8f6f4 v[96:99], v[0:7], v[218:225], v[96:99], v240, v240 op_sel_hi:[0,0,0]
	s_setprio 0
	s_barrier
	v_lshl_add_u64 v[166:167], s[16:17], 0, v[184:185]
	s_add_i32 s16, s60, s6
	s_mov_b32 m0, s16
	ds_read_b128 v[194:197], v176 offset:16384
	ds_read_b128 v[198:201], v176 offset:17408
	ds_read_b128 v[202:205], v176 offset:18432
	ds_read_b128 v[206:209], v176 offset:19456
	ds_read_b128 v[210:213], v176 offset:20480
	ds_read_b128 v[214:217], v176 offset:21504
	ds_read_b128 v[218:221], v176 offset:22528
	ds_read_b128 v[222:225], v176 offset:23552
	global_load_lds_dwordx4 v[166:167], off
	v_lshl_add_u64 v[168:169], v[166:167], 0, s[94:95]
	s_add_i32 m0, s16, 0x2000
	s_add_i32 s16, s61, s6
	global_load_lds_dwordx4 v[168:169], off
	v_lshl_add_u64 v[168:169], v[166:167], 0, s[34:35]
	s_mov_b32 m0, s16
	s_nop 0
	global_load_lds_dwordx4 v[168:169], off
	v_lshl_add_u64 v[168:169], v[166:167], 0, s[90:91]
	s_add_i32 m0, s16, 0x2000
	s_nop 0
	global_load_lds_dwordx4 v[168:169], off
	v_lshl_add_u64 v[168:169], s[14:15], 0, v[160:161]
	s_mov_b32 m0, s19
	v_lshl_add_u64 v[178:179], v[168:169], 0, s[94:95]
	global_load_lds_dwordx4 v[168:169], off
	s_mov_b32 m0, s20
	s_nop 0
	global_load_lds_dwordx4 v[178:179], off
	s_cmp_eq_u32 s98, 0
	s_cbranch_scc0 .Lrlx503_b
	s_waitcnt vmcnt(8)
.Lrlx503_b_back:
	s_waitcnt lgkmcnt(0)
	s_barrier
	s_setprio 1
	s_waitcnt lgkmcnt(0)
	v_mfma_scale_f32_16x16x128_f8f6f4 v[92:95], v[24:31], v[194:201], v[92:95], v240, v240 op_sel_hi:[0,0,0]
	v_mfma_scale_f32_16x16x128_f8f6f4 v[84:87], v[16:23], v[194:201], v[84:87], v240, v240 op_sel_hi:[0,0,0]
	v_mfma_scale_f32_16x16x128_f8f6f4 v[76:79], v[24:31], v[202:209], v[76:79], v240, v240 op_sel_hi:[0,0,0]
	v_mfma_scale_f32_16x16x128_f8f6f4 v[68:71], v[16:23], v[202:209], v[68:71], v240, v240 op_sel_hi:[0,0,0]
	v_mfma_scale_f32_16x16x128_f8f6f4 v[60:63], v[24:31], v[210:217], v[60:63], v240, v240 op_sel_hi:[0,0,0]
	v_mfma_scale_f32_16x16x128_f8f6f4 v[52:55], v[16:23], v[210:217], v[52:55], v240, v240 op_sel_hi:[0,0,0]
	v_mfma_scale_f32_16x16x128_f8f6f4 v[44:47], v[24:31], v[218:225], v[44:47], v240, v240 op_sel_hi:[0,0,0]
	v_mfma_scale_f32_16x16x128_f8f6f4 v[36:39], v[16:23], v[218:225], v[36:39], v240, v240 op_sel_hi:[0,0,0]
	s_setprio 0
	s_setprio 1
	v_mfma_scale_f32_16x16x128_f8f6f4 v[88:91], v[8:15], v[194:201], v[88:91], v240, v240 op_sel_hi:[0,0,0]
	v_mfma_scale_f32_16x16x128_f8f6f4 v[80:83], v[0:7], v[194:201], v[80:83], v240, v240 op_sel_hi:[0,0,0]
	v_mfma_scale_f32_16x16x128_f8f6f4 v[72:75], v[8:15], v[202:209], v[72:75], v240, v240 op_sel_hi:[0,0,0]
	v_mfma_scale_f32_16x16x128_f8f6f4 v[64:67], v[0:7], v[202:209], v[64:67], v240, v240 op_sel_hi:[0,0,0]
	v_mfma_scale_f32_16x16x128_f8f6f4 v[56:59], v[8:15], v[210:217], v[56:59], v240, v240 op_sel_hi:[0,0,0]
	v_mfma_scale_f32_16x16x128_f8f6f4 v[48:51], v[0:7], v[210:217], v[48:51], v240, v240 op_sel_hi:[0,0,0]
	v_mfma_scale_f32_16x16x128_f8f6f4 v[40:43], v[8:15], v[218:225], v[40:43], v240, v240 op_sel_hi:[0,0,0]
	v_mfma_scale_f32_16x16x128_f8f6f4 v[32:35], v[0:7], v[218:225], v[32:35], v240, v240 op_sel_hi:[0,0,0]
	s_setprio 0
	s_barrier
	s_add_i32 s14, 0, 0x18000
	s_add_i32 s15, 0, 0x1c000
	v_add_u32_e32 v12, s14, v172
	v_add_u32_e32 v28, s15, v172
	ds_read_b128 v[0:3], v12
	ds_read_b128 v[4:7], v12 offset:1024
	ds_read_b128 v[8:11], v12 offset:2048
	ds_read_b128 v[12:15], v12 offset:3072
	ds_read_b128 v[16:19], v28
	ds_read_b128 v[20:23], v28 offset:1024
	ds_read_b128 v[24:27], v28 offset:2048
	ds_read_b128 v[28:31], v28 offset:3072
	s_mov_b32 m0, s24
	v_lshl_add_u64 v[178:179], v[168:169], 0, s[34:35]
	ds_read_b128 v[194:197], v176 offset:32768
	ds_read_b128 v[198:201], v176 offset:33792
	ds_read_b128 v[202:205], v176 offset:34816
	ds_read_b128 v[206:209], v176 offset:35840
	ds_read_b128 v[210:213], v176 offset:36864
	ds_read_b128 v[214:217], v176 offset:37888
	ds_read_b128 v[218:221], v176 offset:38912
	ds_read_b128 v[222:225], v176 offset:39936
	global_load_lds_dwordx4 v[178:179], off
	v_lshl_add_u64 v[178:179], v[168:169], 0, s[90:91]
	s_mov_b32 m0, s25
	s_nop 0
	global_load_lds_dwordx4 v[178:179], off
	s_waitcnt vmcnt(8)
	s_waitcnt lgkmcnt(0)
	s_barrier
	s_setprio 1
	s_waitcnt lgkmcnt(0)
	v_mfma_scale_f32_16x16x128_f8f6f4 v[156:159], v[0:7], v[194:201], v[156:159], v240, v240 op_sel_hi:[0,0,0]
	v_mfma_scale_f32_16x16x128_f8f6f4 v[148:151], v[8:15], v[194:201], v[148:151], v240, v240 op_sel_hi:[0,0,0]
	v_mfma_scale_f32_16x16x128_f8f6f4 v[140:143], v[0:7], v[202:209], v[140:143], v240, v240 op_sel_hi:[0,0,0]
	v_mfma_scale_f32_16x16x128_f8f6f4 v[132:135], v[8:15], v[202:209], v[132:135], v240, v240 op_sel_hi:[0,0,0]
	v_mfma_scale_f32_16x16x128_f8f6f4 v[124:127], v[0:7], v[210:217], v[124:127], v240, v240 op_sel_hi:[0,0,0]
	v_mfma_scale_f32_16x16x128_f8f6f4 v[116:119], v[8:15], v[210:217], v[116:119], v240, v240 op_sel_hi:[0,0,0]
	v_mfma_scale_f32_16x16x128_f8f6f4 v[108:111], v[0:7], v[218:225], v[108:111], v240, v240 op_sel_hi:[0,0,0]
	v_mfma_scale_f32_16x16x128_f8f6f4 v[100:103], v[8:15], v[218:225], v[100:103], v240, v240 op_sel_hi:[0,0,0]
	s_setprio 0
	s_setprio 1
	v_mfma_scale_f32_16x16x128_f8f6f4 v[152:155], v[16:23], v[194:201], v[152:155], v240, v240 op_sel_hi:[0,0,0]
	v_mfma_scale_f32_16x16x128_f8f6f4 v[144:147], v[24:31], v[194:201], v[144:147], v240, v240 op_sel_hi:[0,0,0]
	v_mfma_scale_f32_16x16x128_f8f6f4 v[136:139], v[16:23], v[202:209], v[136:139], v240, v240 op_sel_hi:[0,0,0]
	v_mfma_scale_f32_16x16x128_f8f6f4 v[128:131], v[24:31], v[202:209], v[128:131], v240, v240 op_sel_hi:[0,0,0]
	v_mfma_scale_f32_16x16x128_f8f6f4 v[120:123], v[16:23], v[210:217], v[120:123], v240, v240 op_sel_hi:[0,0,0]
	v_mfma_scale_f32_16x16x128_f8f6f4 v[112:115], v[24:31], v[210:217], v[112:115], v240, v240 op_sel_hi:[0,0,0]
	v_mfma_scale_f32_16x16x128_f8f6f4 v[104:107], v[16:23], v[218:225], v[104:107], v240, v240 op_sel_hi:[0,0,0]
	v_mfma_scale_f32_16x16x128_f8f6f4 v[96:99], v[24:31], v[218:225], v[96:99], v240, v240 op_sel_hi:[0,0,0]
	s_setprio 0
	s_barrier
	s_add_i32 s14, s14, s6
	v_lshl_add_u64 v[178:179], v[166:167], 0, s[56:57]
	s_mov_b32 m0, s14
	ds_read_b128 v[194:197], v176 offset:49152
	ds_read_b128 v[198:201], v176 offset:50176
	ds_read_b128 v[202:205], v176 offset:51200
	ds_read_b128 v[206:209], v176 offset:52224
	ds_read_b128 v[210:213], v176 offset:53248
	ds_read_b128 v[214:217], v176 offset:54272
	ds_read_b128 v[218:221], v176 offset:55296
	ds_read_b128 v[222:225], v176 offset:56320
	global_load_lds_dwordx4 v[178:179], off
	v_lshl_add_u64 v[178:179], v[166:167], 0, s[58:59]
	s_add_i32 m0, s14, 0x2000
	s_add_i32 s14, s15, s6
	global_load_lds_dwordx4 v[178:179], off
	v_lshl_add_u64 v[178:179], v[166:167], 0, s[96:97]
	s_mov_b32 m0, s14
	v_lshl_add_u64 v[166:167], v[166:167], 0, s[4:5]
	global_load_lds_dwordx4 v[178:179], off
	s_add_i32 m0, s14, 0x2000
	s_nop 0
	global_load_lds_dwordx4 v[166:167], off
	v_lshl_add_u64 v[166:167], v[168:169], 0, s[56:57]
	s_mov_b32 m0, s26
	s_nop 0
	global_load_lds_dwordx4 v[166:167], off
	v_lshl_add_u64 v[166:167], v[168:169], 0, s[58:59]
	s_mov_b32 m0, s27
	s_nop 0
	global_load_lds_dwordx4 v[166:167], off
	s_waitcnt vmcnt(8)
	s_waitcnt lgkmcnt(0)
	s_barrier
	s_setprio 1
	s_waitcnt lgkmcnt(0)
	v_mfma_scale_f32_16x16x128_f8f6f4 v[92:95], v[0:7], v[194:201], v[92:95], v240, v240 op_sel_hi:[0,0,0]
	v_mfma_scale_f32_16x16x128_f8f6f4 v[84:87], v[8:15], v[194:201], v[84:87], v240, v240 op_sel_hi:[0,0,0]
	v_mfma_scale_f32_16x16x128_f8f6f4 v[76:79], v[0:7], v[202:209], v[76:79], v240, v240 op_sel_hi:[0,0,0]
	v_mfma_scale_f32_16x16x128_f8f6f4 v[68:71], v[8:15], v[202:209], v[68:71], v240, v240 op_sel_hi:[0,0,0]
	v_mfma_scale_f32_16x16x128_f8f6f4 v[60:63], v[0:7], v[210:217], v[60:63], v240, v240 op_sel_hi:[0,0,0]
	v_mfma_scale_f32_16x16x128_f8f6f4 v[52:55], v[8:15], v[210:217], v[52:55], v240, v240 op_sel_hi:[0,0,0]
	v_mfma_scale_f32_16x16x128_f8f6f4 v[44:47], v[0:7], v[218:225], v[44:47], v240, v240 op_sel_hi:[0,0,0]
	v_mfma_scale_f32_16x16x128_f8f6f4 v[36:39], v[8:15], v[218:225], v[36:39], v240, v240 op_sel_hi:[0,0,0]
	s_setprio 0
	s_setprio 1
	v_mfma_scale_f32_16x16x128_f8f6f4 v[88:91], v[16:23], v[194:201], v[88:91], v240, v240 op_sel_hi:[0,0,0]
	v_mfma_scale_f32_16x16x128_f8f6f4 v[80:83], v[24:31], v[194:201], v[80:83], v240, v240 op_sel_hi:[0,0,0]
	v_mfma_scale_f32_16x16x128_f8f6f4 v[72:75], v[16:23], v[202:209], v[72:75], v240, v240 op_sel_hi:[0,0,0]
	v_mfma_scale_f32_16x16x128_f8f6f4 v[64:67], v[24:31], v[202:209], v[64:67], v240, v240 op_sel_hi:[0,0,0]
	v_mfma_scale_f32_16x16x128_f8f6f4 v[56:59], v[16:23], v[210:217], v[56:59], v240, v240 op_sel_hi:[0,0,0]
	v_mfma_scale_f32_16x16x128_f8f6f4 v[48:51], v[24:31], v[210:217], v[48:51], v240, v240 op_sel_hi:[0,0,0]
	v_mfma_scale_f32_16x16x128_f8f6f4 v[40:43], v[16:23], v[218:225], v[40:43], v240, v240 op_sel_hi:[0,0,0]
	v_mfma_scale_f32_16x16x128_f8f6f4 v[32:35], v[24:31], v[218:225], v[32:35], v240, v240 op_sel_hi:[0,0,0]
	s_setprio 0
	s_barrier
	s_add_i32 s51, s51, 2
	s_add_u32 s46, s46, 0x100
	s_addc_u32 s47, s47, 0
	s_add_u32 s49, s49, 0x100
	s_addc_u32 s50, s50, 0
	s_cmp_gt_u32 s51, 5
	s_cbranch_scc0 .LBB0_503
	s_and_b64 vcc, exec, s[8:9]
	s_cbranch_vccz .LBB0_506
	s_barrier

	.amdhsa_kernel _Z14fwd_megakernel4Args
		.amdhsa_group_segment_fixed_size 0
		.amdhsa_private_segment_fixed_size 0
		.amdhsa_kernarg_size 416
		.amdhsa_user_sgpr_count 2
		.amdhsa_user_sgpr_dispatch_ptr 0
		.amdhsa_user_sgpr_queue_ptr 0
		.amdhsa_user_sgpr_kernarg_segment_ptr 1
		.amdhsa_user_sgpr_dispatch_id 0
		.amdhsa_user_sgpr_kernarg_preload_length 0
		.amdhsa_user_sgpr_kernarg_preload_offset 0
		.amdhsa_user_sgpr_private_segment_size 0
		.amdhsa_uses_dynamic_stack 0
		.amdhsa_enable_private_segment 0
		.amdhsa_system_sgpr_workgroup_id_x 1
		.amdhsa_system_sgpr_workgroup_id_y 0
		.amdhsa_system_sgpr_workgroup_id_z 0
		.amdhsa_system_sgpr_workgroup_info 0
		.amdhsa_system_vgpr_workitem_id 2
		.amdhsa_next_free_vgpr 256
		.amdhsa_next_free_sgpr 99
		.amdhsa_accum_offset 256
		.amdhsa_reserve_vcc 1
		.amdhsa_float_round_mode_32 0
		.amdhsa_float_round_mode_16_64 0
		.amdhsa_float_denorm_mode_32 3
		.amdhsa_float_denorm_mode_16_64 3
		.amdhsa_dx10_clamp 1
		.amdhsa_ieee_mode 1
		.amdhsa_fp16_overflow 0
		.amdhsa_tg_split 0
		.amdhsa_exception_fp_ieee_invalid_op 0
		.amdhsa_exception_fp_denorm_src 0
		.amdhsa_exception_fp_ieee_div_zero 0
		.amdhsa_exception_fp_ieee_overflow 0
		.amdhsa_exception_fp_ieee_underflow 0
		.amdhsa_exception_fp_ieee_inexact 0
		.amdhsa_exception_int_div_zero 0
	.end_amdhsa_kernel

amdhsa.kernels:
  - .agpr_count:     0
    .args:
      - .offset:         0
        .size:           160
        .value_kind:     by_value
      - .offset:         160
        .size:           4
        .value_kind:     hidden_block_count_x
      - .offset:         164
        .size:           4
        .value_kind:     hidden_block_count_y
      - .offset:         168
        .size:           4
        .value_kind:     hidden_block_count_z
      - .offset:         172
        .size:           2
        .value_kind:     hidden_group_size_x
      - .offset:         174
        .size:           2
        .value_kind:     hidden_group_size_y
      - .offset:         176
        .size:           2
        .value_kind:     hidden_group_size_z
      - .offset:         178
        .size:           2
        .value_kind:     hidden_remainder_x
      - .offset:         180
        .size:           2
        .value_kind:     hidden_remainder_y
      - .offset:         182
        .size:           2
        .value_kind:     hidden_remainder_z
      - .offset:         200
        .size:           8
        .value_kind:     hidden_global_offset_x
      - .offset:         208
        .size:           8
        .value_kind:     hidden_global_offset_y
      - .offset:         216
        .size:           8
        .value_kind:     hidden_global_offset_z
      - .offset:         224
        .size:           2
        .value_kind:     hidden_grid_dims
      - .offset:         248
        .size:           8
        .value_kind:     hidden_multigrid_sync_arg
      - .offset:         280
        .size:           4
        .value_kind:     hidden_dynamic_lds_size
    .group_segment_fixed_size: 0
    .kernarg_segment_align: 8
    .kernarg_segment_size: 416
    .language:       OpenCL C
    .language_version:
      - 2
      - 0
    .max_flat_workgroup_size: 512
    .name:           _Z14fwd_megakernel4Args
    .private_segment_fixed_size: 0
    .sgpr_count:     105
    .sgpr_spill_count: 202
    .symbol:         _Z14fwd_megakernel4Args.kd
    .uniform_work_group_size: 1
    .uses_dynamic_stack: false
    .vgpr_count:     256
    .vgpr_spill_count: 0
    .wavefront_size: 64
